# GEMM k-loop tail: loop-advance scalar code before the counted wait+barrier, one taken branch per k-step
# speedup vs baseline: 1.0020x; 1.0020x over previous
; template <int EPI>
; __device__ __forceinline__ void gemm_phase(const u16* __restrict__ A0, int nksA, size_t sA, const u16* __restrict__ B0, int nksB, size_t sB,
;                                            int K, int nM, int nN, int nbatch, const EpiArgs ea, char* smem, int bid, int nblk) {
;     ...
;     for (int kk = 0; kk < nk; ++kk) {
;       const bool more = kk + 2 < nk;
;       if (more) GSTAGE(kk + 2, nbuf);
;       bf16x8 Bl[4], At[8];
;       {
;         const int bb = sb0 + buf * 8192, ab = sa0 + buf * 16384;
;         asm volatile(
;             "ds_read_b128 %0, %12\n\tds_read_b128 %1, %12 offset:1024\n\tds_read_b128 %2, %12 offset:2048\n\tds_read_b128 %3, %12 offset:3072\n\t"
;             "ds_read_b128 %4, %13\n\tds_read_b128 %5, %13 offset:1024\n\tds_read_b128 %6, %13 offset:2048\n\tds_read_b128 %7, %13 offset:3072\n\t"
;             "ds_read_b128 %8, %13 offset:4096\n\tds_read_b128 %9, %13 offset:5120\n\tds_read_b128 %10, %13 offset:6144\n\tds_read_b128 %11, %13 offset:7168\n\t"
;             "s_waitcnt lgkmcnt(4)"
;             : "=&v"(Bl[0]), "=&v"(Bl[1]), "=&v"(Bl[2]), "=&v"(Bl[3]), "=&v"(At[0]), "=&v"(At[1]), "=&v"(At[2]), "=&v"(At[3]),
;               "=&v"(At[4]), "=&v"(At[5]), "=&v"(At[6]), "=&v"(At[7])
;             : "v"(bb), "v"(ab)
;             : "memory");
;       }
;       __builtin_amdgcn_s_setprio(1);
; #pragma unroll
;       for (int m = 0; m < 4; ++m)
; #pragma unroll
;         for (int n = 0; n < 4; ++n) acc[m][n] = __builtin_amdgcn_mfma_f32_16x16x32_bf16(Bl[n], At[m], acc[m][n], 0, 0, 0);
;       __builtin_amdgcn_sched_barrier(0);
;       asm volatile("s_waitcnt lgkmcnt(0)" : "+v"(At[4]), "+v"(At[5]), "+v"(At[6]), "+v"(At[7]) :: "memory");
;       __builtin_amdgcn_sched_barrier(0);
; #pragma unroll
;       for (int m = 4; m < 8; ++m)
; #pragma unroll
;         for (int n = 0; n < 4; ++n) acc[m][n] = __builtin_amdgcn_mfma_f32_16x16x32_bf16(Bl[n], At[m], acc[m][n], 0, 0, 0);
;       __builtin_amdgcn_s_setprio(0);
;       if (more) asm volatile("s_waitcnt vmcnt(6)\n\ts_barrier" ::: "memory");
;       else asm volatile("s_waitcnt vmcnt(0)\n\ts_barrier" ::: "memory");
;       buf = (buf == 2) ? 0 : buf + 1; nbuf = (nbuf == 2) ? 0 : nbuf + 1;
;     }
.LBB0_183:
	v_lshl_add_u32 v134, s89, 13, v148
	v_lshl_add_u32 v165, s89, 14, v147
	ds_read_b128 v[136:139], v134
	ds_read_b128 v[140:143], v134 offset:1024
	ds_read_b128 v[166:169], v134 offset:2048
	ds_read_b128 v[170:173], v134 offset:3072
	ds_read_b128 v[174:177], v165
	ds_read_b128 v[178:181], v165 offset:1024
	ds_read_b128 v[182:185], v165 offset:2048
	ds_read_b128 v[186:189], v165 offset:3072
	ds_read_b128 v[190:193], v165 offset:4096
	ds_read_b128 v[194:197], v165 offset:5120
	ds_read_b128 v[200:203], v165 offset:6144
	ds_read_b128 v[204:207], v165 offset:7168
	s_waitcnt lgkmcnt(7)
	s_setprio 1
	v_mfma_f32_16x16x32_bf16 v[124:127], v[136:139], v[174:177], v[124:127]
	v_mfma_f32_16x16x32_bf16 v[120:123], v[140:143], v[174:177], v[120:123]
	v_mfma_f32_16x16x32_bf16 v[116:119], v[166:169], v[174:177], v[116:119]
	v_mfma_f32_16x16x32_bf16 v[112:115], v[170:173], v[174:177], v[112:115]
	s_waitcnt lgkmcnt(6)
	v_mfma_f32_16x16x32_bf16 v[108:111], v[136:139], v[178:181], v[108:111]
	v_mfma_f32_16x16x32_bf16 v[104:107], v[140:143], v[178:181], v[104:107]
	v_mfma_f32_16x16x32_bf16 v[100:103], v[166:169], v[178:181], v[100:103]
	v_mfma_f32_16x16x32_bf16 v[96:99], v[170:173], v[178:181], v[96:99]
	s_waitcnt lgkmcnt(5)
	v_mfma_f32_16x16x32_bf16 v[92:95], v[136:139], v[182:185], v[92:95]
	v_mfma_f32_16x16x32_bf16 v[88:91], v[140:143], v[182:185], v[88:91]
	v_mfma_f32_16x16x32_bf16 v[84:87], v[166:169], v[182:185], v[84:87]
	v_mfma_f32_16x16x32_bf16 v[80:83], v[170:173], v[182:185], v[80:83]
	s_waitcnt lgkmcnt(4)
	v_mfma_f32_16x16x32_bf16 v[76:79], v[136:139], v[186:189], v[76:79]
	v_mfma_f32_16x16x32_bf16 v[72:75], v[140:143], v[186:189], v[72:75]
	v_mfma_f32_16x16x32_bf16 v[68:71], v[166:169], v[186:189], v[68:71]
	v_mfma_f32_16x16x32_bf16 v[64:67], v[170:173], v[186:189], v[64:67]
	s_waitcnt lgkmcnt(3)
	s_nop 0
	v_mfma_f32_16x16x32_bf16 v[60:63], v[136:139], v[190:193], v[60:63]
	v_mfma_f32_16x16x32_bf16 v[56:59], v[140:143], v[190:193], v[56:59]
	v_mfma_f32_16x16x32_bf16 v[52:55], v[166:169], v[190:193], v[52:55]
	v_mfma_f32_16x16x32_bf16 v[48:51], v[170:173], v[190:193], v[48:51]
	s_waitcnt lgkmcnt(2)
	v_mfma_f32_16x16x32_bf16 v[44:47], v[136:139], v[194:197], v[44:47]
	v_mfma_f32_16x16x32_bf16 v[40:43], v[140:143], v[194:197], v[40:43]
	v_mfma_f32_16x16x32_bf16 v[36:39], v[166:169], v[194:197], v[36:39]
	v_mfma_f32_16x16x32_bf16 v[32:35], v[170:173], v[194:197], v[32:35]
	s_waitcnt lgkmcnt(1)
	v_mfma_f32_16x16x32_bf16 v[28:31], v[136:139], v[200:203], v[28:31]
	v_mfma_f32_16x16x32_bf16 v[24:27], v[140:143], v[200:203], v[24:27]
	v_mfma_f32_16x16x32_bf16 v[16:19], v[166:169], v[200:203], v[16:19]
	v_mfma_f32_16x16x32_bf16 v[4:7], v[170:173], v[200:203], v[4:7]
	s_waitcnt lgkmcnt(0)
	v_mfma_f32_16x16x32_bf16 v[20:23], v[136:139], v[204:207], v[20:23]
	v_mfma_f32_16x16x32_bf16 v[12:15], v[140:143], v[204:207], v[12:15]
	v_mfma_f32_16x16x32_bf16 v[8:11], v[166:169], v[204:207], v[8:11]
	v_mfma_f32_16x16x32_bf16 v[0:3], v[170:173], v[204:207], v[0:3]
	s_setprio 0
	s_and_b64 vcc, exec, s[64:65]
	s_cbranch_vccnz .Lgt0_last
	s_add_i32 s36, s89, 1
	s_cmp_lg_u32 s89, 2
	s_cselect_b32 s89, s36, 0
	s_add_i32 s36, s31, 1
	s_cmp_lg_u32 s31, 2
	s_cselect_b32 s31, s36, 0
	s_add_i32 s5, s5, 1
	s_add_u32 s56, s56, 0x2000
	s_addc_u32 s57, s57, 0
	s_add_u32 s58, s58, 0x4000
	s_addc_u32 s59, s59, 0
	s_cmp_eq_u32 s5, 32
	s_waitcnt vmcnt(6)
	s_barrier
	s_branch .LBB0_181
.Lgt0_last:
	s_waitcnt vmcnt(0)
	s_barrier
	s_branch .LBB0_180

; template <int EPI>
; __device__ __forceinline__ void gemm_phase(const u16* __restrict__ A0, int nksA, size_t sA, const u16* __restrict__ B0, int nksB, size_t sB,
;                                            int K, int nM, int nN, int nbatch, const EpiArgs ea, char* smem, int bid, int nblk) {
;     ...
;     for (int kk = 0; kk < nk; ++kk) {
;       const bool more = kk + 2 < nk;
;       if (more) GSTAGE(kk + 2, nbuf);
;       bf16x8 Bl[4], At[8];
;       {
;         const int bb = sb0 + buf * 8192, ab = sa0 + buf * 16384;
;         asm volatile(
;             "ds_read_b128 %0, %12\n\tds_read_b128 %1, %12 offset:1024\n\tds_read_b128 %2, %12 offset:2048\n\tds_read_b128 %3, %12 offset:3072\n\t"
;             "ds_read_b128 %4, %13\n\tds_read_b128 %5, %13 offset:1024\n\tds_read_b128 %6, %13 offset:2048\n\tds_read_b128 %7, %13 offset:3072\n\t"
;             "ds_read_b128 %8, %13 offset:4096\n\tds_read_b128 %9, %13 offset:5120\n\tds_read_b128 %10, %13 offset:6144\n\tds_read_b128 %11, %13 offset:7168\n\t"
;             "s_waitcnt lgkmcnt(4)"
;             : "=&v"(Bl[0]), "=&v"(Bl[1]), "=&v"(Bl[2]), "=&v"(Bl[3]), "=&v"(At[0]), "=&v"(At[1]), "=&v"(At[2]), "=&v"(At[3]),
;               "=&v"(At[4]), "=&v"(At[5]), "=&v"(At[6]), "=&v"(At[7])
;             : "v"(bb), "v"(ab)
;             : "memory");
;       }
;       __builtin_amdgcn_s_setprio(1);
; #pragma unroll
;       for (int m = 0; m < 4; ++m)
; #pragma unroll
;         for (int n = 0; n < 4; ++n) acc[m][n] = __builtin_amdgcn_mfma_f32_16x16x32_bf16(Bl[n], At[m], acc[m][n], 0, 0, 0);
;       __builtin_amdgcn_sched_barrier(0);
;       asm volatile("s_waitcnt lgkmcnt(0)" : "+v"(At[4]), "+v"(At[5]), "+v"(At[6]), "+v"(At[7]) :: "memory");
;       __builtin_amdgcn_sched_barrier(0);
; #pragma unroll
;       for (int m = 4; m < 8; ++m)
; #pragma unroll
;         for (int n = 0; n < 4; ++n) acc[m][n] = __builtin_amdgcn_mfma_f32_16x16x32_bf16(Bl[n], At[m], acc[m][n], 0, 0, 0);
;       __builtin_amdgcn_s_setprio(0);
;       if (more) asm volatile("s_waitcnt vmcnt(6)\n\ts_barrier" ::: "memory");
;       else asm volatile("s_waitcnt vmcnt(0)\n\ts_barrier" ::: "memory");
;       buf = (buf == 2) ? 0 : buf + 1; nbuf = (nbuf == 2) ? 0 : nbuf + 1;
;     }
.LBB0_386:
	v_lshl_add_u32 v196, s90, 13, v135
	v_lshl_add_u32 v197, s90, 14, v134
	ds_read_b128 v[148:151], v196
	ds_read_b128 v[152:155], v196 offset:1024
	ds_read_b128 v[156:159], v196 offset:2048
	ds_read_b128 v[160:163], v196 offset:3072
	ds_read_b128 v[164:167], v197
	ds_read_b128 v[168:171], v197 offset:1024
	ds_read_b128 v[172:175], v197 offset:2048
	ds_read_b128 v[176:179], v197 offset:3072
	ds_read_b128 v[180:183], v197 offset:4096
	ds_read_b128 v[184:187], v197 offset:5120
	ds_read_b128 v[188:191], v197 offset:6144
	ds_read_b128 v[192:195], v197 offset:7168
	s_waitcnt lgkmcnt(7)
	s_setprio 1
	v_mfma_f32_16x16x32_bf16 v[124:127], v[148:151], v[164:167], v[124:127]
	v_mfma_f32_16x16x32_bf16 v[120:123], v[152:155], v[164:167], v[120:123]
	v_mfma_f32_16x16x32_bf16 v[116:119], v[156:159], v[164:167], v[116:119]
	v_mfma_f32_16x16x32_bf16 v[112:115], v[160:163], v[164:167], v[112:115]
	s_waitcnt lgkmcnt(6)
	v_mfma_f32_16x16x32_bf16 v[108:111], v[148:151], v[168:171], v[108:111]
	v_mfma_f32_16x16x32_bf16 v[104:107], v[152:155], v[168:171], v[104:107]
	v_mfma_f32_16x16x32_bf16 v[100:103], v[156:159], v[168:171], v[100:103]
	v_mfma_f32_16x16x32_bf16 v[96:99], v[160:163], v[168:171], v[96:99]
	s_waitcnt lgkmcnt(5)
	v_mfma_f32_16x16x32_bf16 v[92:95], v[148:151], v[172:175], v[92:95]
	v_mfma_f32_16x16x32_bf16 v[88:91], v[152:155], v[172:175], v[88:91]
	v_mfma_f32_16x16x32_bf16 v[80:83], v[156:159], v[172:175], v[80:83]
	v_mfma_f32_16x16x32_bf16 v[72:75], v[160:163], v[172:175], v[72:75]
	s_waitcnt lgkmcnt(4)
	v_mfma_f32_16x16x32_bf16 v[60:63], v[148:151], v[176:179], v[60:63]
	v_mfma_f32_16x16x32_bf16 v[56:59], v[152:155], v[176:179], v[56:59]
	v_mfma_f32_16x16x32_bf16 v[52:55], v[156:159], v[176:179], v[52:55]
	v_mfma_f32_16x16x32_bf16 v[48:51], v[160:163], v[176:179], v[48:51]
	s_waitcnt lgkmcnt(3)
	s_nop 0
	v_mfma_f32_16x16x32_bf16 v[44:47], v[148:151], v[180:183], v[44:47]
	v_mfma_f32_16x16x32_bf16 v[40:43], v[152:155], v[180:183], v[40:43]
	v_mfma_f32_16x16x32_bf16 v[36:39], v[156:159], v[180:183], v[36:39]
	v_mfma_f32_16x16x32_bf16 v[32:35], v[160:163], v[180:183], v[32:35]
	s_waitcnt lgkmcnt(2)
	v_mfma_f32_16x16x32_bf16 v[28:31], v[148:151], v[184:187], v[28:31]
	v_mfma_f32_16x16x32_bf16 v[24:27], v[152:155], v[184:187], v[24:27]
	v_mfma_f32_16x16x32_bf16 v[20:23], v[156:159], v[184:187], v[20:23]
	v_mfma_f32_16x16x32_bf16 v[16:19], v[160:163], v[184:187], v[16:19]
	s_waitcnt lgkmcnt(1)
	v_mfma_f32_16x16x32_bf16 v[12:15], v[148:151], v[188:191], v[12:15]
	v_mfma_f32_16x16x32_bf16 v[8:11], v[152:155], v[188:191], v[8:11]
	v_mfma_f32_16x16x32_bf16 v[4:7], v[156:159], v[188:191], v[4:7]
	v_mfma_f32_16x16x32_bf16 v[0:3], v[160:163], v[188:191], v[0:3]
	s_waitcnt lgkmcnt(0)
	v_mfma_f32_16x16x32_bf16 v[64:67], v[148:151], v[192:195], v[64:67]
	v_mfma_f32_16x16x32_bf16 v[68:71], v[152:155], v[192:195], v[68:71]
	v_mfma_f32_16x16x32_bf16 v[76:79], v[156:159], v[192:195], v[76:79]
	v_mfma_f32_16x16x32_bf16 v[84:87], v[160:163], v[192:195], v[84:87]
	s_setprio 0
	s_and_b64 vcc, exec, s[80:81]
	s_cbranch_vccnz .Lgt1_last
	s_add_i32 s36, s90, 1
	s_cmp_lg_u32 s90, 2
	s_cselect_b32 s90, s36, 0
	s_add_i32 s36, s87, 1
	s_cmp_lg_u32 s87, 2
	s_cselect_b32 s87, s36, 0
	s_add_i32 s89, s89, 1
	s_add_u32 s64, s64, 0x2000
	s_addc_u32 s65, s65, 0
	s_add_u32 s66, s66, 0x4000
	s_addc_u32 s67, s67, 0
	s_cmp_eq_u32 s89, 16
	s_waitcnt vmcnt(6)
	s_barrier
	s_branch .LBB0_384

; template <int EPI>
; __device__ __forceinline__ void gemm_phase(const u16* __restrict__ A0, int nksA, size_t sA, const u16* __restrict__ B0, int nksB, size_t sB,
;                                            int K, int nM, int nN, int nbatch, const EpiArgs ea, char* smem, int bid, int nblk) {
;     ...
;     if (EPI == E_S5Y) { klim = 4 * (pn + 1); nk = klim + 4; }
;     f32x4 acc[8][4];
; #pragma unroll
;     for (int m = 0; m < 8; ++m)
; #pragma unroll
;       for (int n = 0; n < 4; ++n) acc[m][n] = f32x4{0.f, 0.f, 0.f, 0.f};
;     ...
;     asm volatile("s_waitcnt vmcnt(0)" ::: "memory");
;     GSTAGE(0, 0);
;     if (nk > 1) { GSTAGE(1, 1); asm volatile("s_waitcnt vmcnt(6)\n\ts_barrier" ::: "memory"); }
;     else { asm volatile("s_waitcnt vmcnt(0)\n\ts_barrier" ::: "memory"); }
;     int buf = 0, nbuf = 2;
; #pragma unroll 1
;     for (int kk = 0; kk < nk; ++kk) {
;       const bool more = kk + 2 < nk;
;       if (more) GSTAGE(kk + 2, nbuf);
;       bf16x8 Bl[4], At[8];
;       {
;         const int bb = sb0 + buf * 8192, ab = sa0 + buf * 16384;
;         asm volatile(
;             "ds_read_b128 %0, %12\n\tds_read_b128 %1, %12 offset:1024\n\tds_read_b128 %2, %12 offset:2048\n\tds_read_b128 %3, %12 offset:3072\n\t"
;             "ds_read_b128 %4, %13\n\tds_read_b128 %5, %13 offset:1024\n\tds_read_b128 %6, %13 offset:2048\n\tds_read_b128 %7, %13 offset:3072\n\t"
;             "ds_read_b128 %8, %13 offset:4096\n\tds_read_b128 %9, %13 offset:5120\n\tds_read_b128 %10, %13 offset:6144\n\tds_read_b128 %11, %13 offset:7168\n\t"
;             "s_waitcnt lgkmcnt(4)"
;             : "=&v"(Bl[0]), "=&v"(Bl[1]), "=&v"(Bl[2]), "=&v"(Bl[3]), "=&v"(At[0]), "=&v"(At[1]), "=&v"(At[2]), "=&v"(At[3]),
;               "=&v"(At[4]), "=&v"(At[5]), "=&v"(At[6]), "=&v"(At[7])
;             : "v"(bb), "v"(ab)
;             : "memory");
;       }
;       __builtin_amdgcn_s_setprio(1);
; #pragma unroll
;       for (int m = 0; m < 4; ++m)
; #pragma unroll
;         for (int n = 0; n < 4; ++n) acc[m][n] = __builtin_amdgcn_mfma_f32_16x16x32_bf16(Bl[n], At[m], acc[m][n], 0, 0, 0);
;       __builtin_amdgcn_sched_barrier(0);
;       asm volatile("s_waitcnt lgkmcnt(0)" : "+v"(At[4]), "+v"(At[5]), "+v"(At[6]), "+v"(At[7]) :: "memory");
;       __builtin_amdgcn_sched_barrier(0);
; #pragma unroll
;       for (int m = 4; m < 8; ++m)
; #pragma unroll
.LBB0_609:
	v_lshl_add_u32 v134, s89, 13, v156
	v_lshl_add_u32 v179, s89, 14, v155
	ds_read_b128 v[142:145], v134
	ds_read_b128 v[146:149], v134 offset:1024
	ds_read_b128 v[150:153], v134 offset:2048
	ds_read_b128 v[180:183], v134 offset:3072
	ds_read_b128 v[184:187], v179
	ds_read_b128 v[188:191], v179 offset:1024
	ds_read_b128 v[192:195], v179 offset:2048
	ds_read_b128 v[200:203], v179 offset:3072
	ds_read_b128 v[204:207], v179 offset:4096
	ds_read_b128 v[208:211], v179 offset:5120
	ds_read_b128 v[212:215], v179 offset:6144
	ds_read_b128 v[216:219], v179 offset:7168
	s_waitcnt lgkmcnt(7)
	s_setprio 1
	v_mfma_f32_16x16x32_bf16 v[124:127], v[142:145], v[184:187], v[124:127]
	v_mfma_f32_16x16x32_bf16 v[120:123], v[146:149], v[184:187], v[120:123]
	v_mfma_f32_16x16x32_bf16 v[116:119], v[150:153], v[184:187], v[116:119]
	v_mfma_f32_16x16x32_bf16 v[112:115], v[180:183], v[184:187], v[112:115]
	s_waitcnt lgkmcnt(6)
	v_mfma_f32_16x16x32_bf16 v[108:111], v[142:145], v[188:191], v[108:111]
	v_mfma_f32_16x16x32_bf16 v[104:107], v[146:149], v[188:191], v[104:107]
	v_mfma_f32_16x16x32_bf16 v[100:103], v[150:153], v[188:191], v[100:103]
	v_mfma_f32_16x16x32_bf16 v[96:99], v[180:183], v[188:191], v[96:99]
	s_waitcnt lgkmcnt(5)
	v_mfma_f32_16x16x32_bf16 v[92:95], v[142:145], v[192:195], v[92:95]
	v_mfma_f32_16x16x32_bf16 v[88:91], v[146:149], v[192:195], v[88:91]
	v_mfma_f32_16x16x32_bf16 v[84:87], v[150:153], v[192:195], v[84:87]
	v_mfma_f32_16x16x32_bf16 v[80:83], v[180:183], v[192:195], v[80:83]
	s_waitcnt lgkmcnt(4)
	v_mfma_f32_16x16x32_bf16 v[76:79], v[142:145], v[200:203], v[76:79]
	v_mfma_f32_16x16x32_bf16 v[72:75], v[146:149], v[200:203], v[72:75]
	v_mfma_f32_16x16x32_bf16 v[68:71], v[150:153], v[200:203], v[68:71]
	v_mfma_f32_16x16x32_bf16 v[64:67], v[180:183], v[200:203], v[64:67]
	s_waitcnt lgkmcnt(3)
	s_nop 0
	v_mfma_f32_16x16x32_bf16 v[60:63], v[142:145], v[204:207], v[60:63]
	v_mfma_f32_16x16x32_bf16 v[56:59], v[146:149], v[204:207], v[56:59]
	v_mfma_f32_16x16x32_bf16 v[52:55], v[150:153], v[204:207], v[52:55]
	v_mfma_f32_16x16x32_bf16 v[48:51], v[180:183], v[204:207], v[48:51]
	s_waitcnt lgkmcnt(2)
	v_mfma_f32_16x16x32_bf16 v[44:47], v[142:145], v[208:211], v[44:47]
	v_mfma_f32_16x16x32_bf16 v[40:43], v[146:149], v[208:211], v[40:43]
	v_mfma_f32_16x16x32_bf16 v[36:39], v[150:153], v[208:211], v[36:39]
	v_mfma_f32_16x16x32_bf16 v[32:35], v[180:183], v[208:211], v[32:35]
	s_waitcnt lgkmcnt(1)
	v_mfma_f32_16x16x32_bf16 v[28:31], v[142:145], v[212:215], v[28:31]
	v_mfma_f32_16x16x32_bf16 v[24:27], v[146:149], v[212:215], v[24:27]
	v_mfma_f32_16x16x32_bf16 v[20:23], v[150:153], v[212:215], v[20:23]
	v_mfma_f32_16x16x32_bf16 v[16:19], v[180:183], v[212:215], v[16:19]
	s_waitcnt lgkmcnt(0)
	v_mfma_f32_16x16x32_bf16 v[12:15], v[142:145], v[216:219], v[12:15]
	v_mfma_f32_16x16x32_bf16 v[8:11], v[146:149], v[216:219], v[8:11]
	v_mfma_f32_16x16x32_bf16 v[4:7], v[150:153], v[216:219], v[4:7]
	v_mfma_f32_16x16x32_bf16 v[0:3], v[180:183], v[216:219], v[0:3]
	s_setprio 0
	s_and_b64 vcc, exec, s[16:17]
	s_cbranch_vccnz .Lgt2_last
	s_add_i32 s16, s89, 1
	s_cmp_lg_u32 s89, 2
	s_cselect_b32 s89, s16, 0
	s_add_i32 s16, s86, 1
	s_cmp_lg_u32 s86, 2
	s_cselect_b32 s86, s16, 0
	s_add_i32 s87, s87, 1
	s_add_i32 s16, s88, s87
	s_cmp_eq_u32 s16, 8
	s_waitcnt vmcnt(6)
	s_barrier
	s_branch .LBB0_607

; template <int EPI>
; __device__ __forceinline__ void gemm_phase(const u16* __restrict__ A0, int nksA, size_t sA, const u16* __restrict__ B0, int nksB, size_t sB,
;                                            int K, int nM, int nN, int nbatch, const EpiArgs ea, char* smem, int bid, int nblk) {
;     ...
;     for (int kk = 0; kk < nk; ++kk) {
;       const bool more = kk + 2 < nk;
;       if (more) GSTAGE(kk + 2, nbuf);
;       bf16x8 Bl[4], At[8];
;       {
;         const int bb = sb0 + buf * 8192, ab = sa0 + buf * 16384;
;         asm volatile(
;             "ds_read_b128 %0, %12\n\tds_read_b128 %1, %12 offset:1024\n\tds_read_b128 %2, %12 offset:2048\n\tds_read_b128 %3, %12 offset:3072\n\t"
;             "ds_read_b128 %4, %13\n\tds_read_b128 %5, %13 offset:1024\n\tds_read_b128 %6, %13 offset:2048\n\tds_read_b128 %7, %13 offset:3072\n\t"
;             "ds_read_b128 %8, %13 offset:4096\n\tds_read_b128 %9, %13 offset:5120\n\tds_read_b128 %10, %13 offset:6144\n\tds_read_b128 %11, %13 offset:7168\n\t"
;             "s_waitcnt lgkmcnt(4)"
;             : "=&v"(Bl[0]), "=&v"(Bl[1]), "=&v"(Bl[2]), "=&v"(Bl[3]), "=&v"(At[0]), "=&v"(At[1]), "=&v"(At[2]), "=&v"(At[3]),
;               "=&v"(At[4]), "=&v"(At[5]), "=&v"(At[6]), "=&v"(At[7])
;             : "v"(bb), "v"(ab)
;             : "memory");
;       }
;       __builtin_amdgcn_s_setprio(1);
; #pragma unroll
;       for (int m = 0; m < 4; ++m)
; #pragma unroll
;         for (int n = 0; n < 4; ++n) acc[m][n] = __builtin_amdgcn_mfma_f32_16x16x32_bf16(Bl[n], At[m], acc[m][n], 0, 0, 0);
;       __builtin_amdgcn_sched_barrier(0);
;       asm volatile("s_waitcnt lgkmcnt(0)" : "+v"(At[4]), "+v"(At[5]), "+v"(At[6]), "+v"(At[7]) :: "memory");
;       __builtin_amdgcn_sched_barrier(0);
; #pragma unroll
;       for (int m = 4; m < 8; ++m)
; #pragma unroll
;         for (int n = 0; n < 4; ++n) acc[m][n] = __builtin_amdgcn_mfma_f32_16x16x32_bf16(Bl[n], At[m], acc[m][n], 0, 0, 0);
;       __builtin_amdgcn_s_setprio(0);
;       if (more) asm volatile("s_waitcnt vmcnt(6)\n\ts_barrier" ::: "memory");
;       else asm volatile("s_waitcnt vmcnt(0)\n\ts_barrier" ::: "memory");
;       buf = (buf == 2) ? 0 : buf + 1; nbuf = (nbuf == 2) ? 0 : nbuf + 1;
;     }
.LBB0_1281:
	v_lshl_add_u32 v147, s43, 13, v183
	v_lshl_add_u32 v149, s43, 14, v182
	ds_read_b128 v[154:157], v147
	ds_read_b128 v[158:161], v147 offset:1024
	ds_read_b128 v[162:165], v147 offset:2048
	ds_read_b128 v[166:169], v147 offset:3072
	ds_read_b128 v[170:173], v149
	ds_read_b128 v[174:177], v149 offset:1024
	ds_read_b128 v[200:203], v149 offset:2048
	ds_read_b128 v[204:207], v149 offset:3072
	ds_read_b128 v[208:211], v149 offset:4096
	ds_read_b128 v[212:215], v149 offset:5120
	ds_read_b128 v[216:219], v149 offset:6144
	ds_read_b128 v[220:223], v149 offset:7168
	s_waitcnt lgkmcnt(7)
	s_setprio 1
	v_mfma_f32_16x16x32_bf16 v[124:127], v[154:157], v[170:173], v[124:127]
	v_mfma_f32_16x16x32_bf16 v[120:123], v[158:161], v[170:173], v[120:123]
	v_mfma_f32_16x16x32_bf16 v[116:119], v[162:165], v[170:173], v[116:119]
	v_mfma_f32_16x16x32_bf16 v[112:115], v[166:169], v[170:173], v[112:115]
	s_waitcnt lgkmcnt(6)
	v_mfma_f32_16x16x32_bf16 v[108:111], v[154:157], v[174:177], v[108:111]
	v_mfma_f32_16x16x32_bf16 v[104:107], v[158:161], v[174:177], v[104:107]
	v_mfma_f32_16x16x32_bf16 v[100:103], v[162:165], v[174:177], v[100:103]
	v_mfma_f32_16x16x32_bf16 v[96:99], v[166:169], v[174:177], v[96:99]
	s_waitcnt lgkmcnt(5)
	v_mfma_f32_16x16x32_bf16 v[92:95], v[154:157], v[200:203], v[92:95]
	v_mfma_f32_16x16x32_bf16 v[88:91], v[158:161], v[200:203], v[88:91]
	v_mfma_f32_16x16x32_bf16 v[84:87], v[162:165], v[200:203], v[84:87]
	v_mfma_f32_16x16x32_bf16 v[80:83], v[166:169], v[200:203], v[80:83]
	s_waitcnt lgkmcnt(4)
	v_mfma_f32_16x16x32_bf16 v[76:79], v[154:157], v[204:207], v[76:79]
	v_mfma_f32_16x16x32_bf16 v[72:75], v[158:161], v[204:207], v[72:75]
	v_mfma_f32_16x16x32_bf16 v[68:71], v[162:165], v[204:207], v[68:71]
	v_mfma_f32_16x16x32_bf16 v[64:67], v[166:169], v[204:207], v[64:67]
	s_waitcnt lgkmcnt(3)
	s_nop 0
	v_mfma_f32_16x16x32_bf16 v[60:63], v[154:157], v[208:211], v[60:63]
	v_mfma_f32_16x16x32_bf16 v[56:59], v[158:161], v[208:211], v[56:59]
	v_mfma_f32_16x16x32_bf16 v[52:55], v[162:165], v[208:211], v[52:55]
	v_mfma_f32_16x16x32_bf16 v[48:51], v[166:169], v[208:211], v[48:51]
	s_waitcnt lgkmcnt(2)
	v_mfma_f32_16x16x32_bf16 v[44:47], v[154:157], v[212:215], v[44:47]
	v_mfma_f32_16x16x32_bf16 v[40:43], v[158:161], v[212:215], v[40:43]
	v_mfma_f32_16x16x32_bf16 v[36:39], v[162:165], v[212:215], v[36:39]
	v_mfma_f32_16x16x32_bf16 v[32:35], v[166:169], v[212:215], v[32:35]
	s_waitcnt lgkmcnt(1)
	v_mfma_f32_16x16x32_bf16 v[28:31], v[154:157], v[216:219], v[28:31]
	v_mfma_f32_16x16x32_bf16 v[24:27], v[158:161], v[216:219], v[24:27]
	v_mfma_f32_16x16x32_bf16 v[20:23], v[162:165], v[216:219], v[20:23]
	v_mfma_f32_16x16x32_bf16 v[12:15], v[166:169], v[216:219], v[12:15]
	s_waitcnt lgkmcnt(0)
	v_mfma_f32_16x16x32_bf16 v[16:19], v[154:157], v[220:223], v[16:19]
	v_mfma_f32_16x16x32_bf16 v[8:11], v[158:161], v[220:223], v[8:11]
	v_mfma_f32_16x16x32_bf16 v[4:7], v[162:165], v[220:223], v[4:7]
	v_mfma_f32_16x16x32_bf16 v[0:3], v[166:169], v[220:223], v[0:3]
	s_setprio 0
	s_and_b64 vcc, exec, s[54:55]
	s_cbranch_vccnz .Lgt3_last
	s_add_i32 s36, s43, 1
	s_cmp_lg_u32 s43, 2
	s_cselect_b32 s43, s36, 0
	s_add_i32 s36, s35, 1
	s_cmp_lg_u32 s35, 2
	s_cselect_b32 s35, s36, 0
	s_add_i32 s49, s49, 1
	s_add_u32 s50, s50, 0x2000
	s_addc_u32 s51, s51, 0
	s_add_u32 s52, s52, 0x4000
	s_addc_u32 s53, s53, 0
	s_cmp_eq_u32 s49, 16
	s_waitcnt vmcnt(6)
	s_barrier
	s_branch .LBB0_1279

; template <int EPI>
; __device__ __forceinline__ void gemm_phase(const u16* __restrict__ A0, int nksA, size_t sA, const u16* __restrict__ B0, int nksB, size_t sB,
;                                            int K, int nM, int nN, int nbatch, const EpiArgs ea, char* smem, int bid, int nblk) {
;     ...
;     for (int kk = 0; kk < nk; ++kk) {
;       const bool more = kk + 2 < nk;
;       if (more) GSTAGE(kk + 2, nbuf);
;       bf16x8 Bl[4], At[8];
;       {
;         const int bb = sb0 + buf * 8192, ab = sa0 + buf * 16384;
;         asm volatile(
;             "ds_read_b128 %0, %12\n\tds_read_b128 %1, %12 offset:1024\n\tds_read_b128 %2, %12 offset:2048\n\tds_read_b128 %3, %12 offset:3072\n\t"
;             "ds_read_b128 %4, %13\n\tds_read_b128 %5, %13 offset:1024\n\tds_read_b128 %6, %13 offset:2048\n\tds_read_b128 %7, %13 offset:3072\n\t"
;             "ds_read_b128 %8, %13 offset:4096\n\tds_read_b128 %9, %13 offset:5120\n\tds_read_b128 %10, %13 offset:6144\n\tds_read_b128 %11, %13 offset:7168\n\t"
;             "s_waitcnt lgkmcnt(4)"
;             : "=&v"(Bl[0]), "=&v"(Bl[1]), "=&v"(Bl[2]), "=&v"(Bl[3]), "=&v"(At[0]), "=&v"(At[1]), "=&v"(At[2]), "=&v"(At[3]),
;               "=&v"(At[4]), "=&v"(At[5]), "=&v"(At[6]), "=&v"(At[7])
;             : "v"(bb), "v"(ab)
;             : "memory");
;       }
;       __builtin_amdgcn_s_setprio(1);
; #pragma unroll
;       for (int m = 0; m < 4; ++m)
; #pragma unroll
;         for (int n = 0; n < 4; ++n) acc[m][n] = __builtin_amdgcn_mfma_f32_16x16x32_bf16(Bl[n], At[m], acc[m][n], 0, 0, 0);
;       __builtin_amdgcn_sched_barrier(0);
;       asm volatile("s_waitcnt lgkmcnt(0)" : "+v"(At[4]), "+v"(At[5]), "+v"(At[6]), "+v"(At[7]) :: "memory");
;       __builtin_amdgcn_sched_barrier(0);
; #pragma unroll
;       for (int m = 4; m < 8; ++m)
; #pragma unroll
;         for (int n = 0; n < 4; ++n) acc[m][n] = __builtin_amdgcn_mfma_f32_16x16x32_bf16(Bl[n], At[m], acc[m][n], 0, 0, 0);
;       __builtin_amdgcn_s_setprio(0);
;       if (more) asm volatile("s_waitcnt vmcnt(6)\n\ts_barrier" ::: "memory");
;       else asm volatile("s_waitcnt vmcnt(0)\n\ts_barrier" ::: "memory");
;       buf = (buf == 2) ? 0 : buf + 1; nbuf = (nbuf == 2) ? 0 : nbuf + 1;
;     }
.LBB0_1356:
	v_lshl_add_u32 v138, s43, 13, v143
	v_lshl_add_u32 v139, s43, 14, v142
	ds_read_b128 v[134:137], v138
	ds_read_b128 v[156:159], v138 offset:1024
	ds_read_b128 v[160:163], v138 offset:2048
	ds_read_b128 v[164:167], v138 offset:3072
	ds_read_b128 v[168:171], v139
	ds_read_b128 v[172:175], v139 offset:1024
	ds_read_b128 v[176:179], v139 offset:2048
	ds_read_b128 v[180:183], v139 offset:3072
	ds_read_b128 v[184:187], v139 offset:4096
	ds_read_b128 v[188:191], v139 offset:5120
	ds_read_b128 v[192:195], v139 offset:6144
	ds_read_b128 v[200:203], v139 offset:7168
	s_waitcnt lgkmcnt(7)
	s_setprio 1
	v_mfma_f32_16x16x32_bf16 v[124:127], v[134:137], v[168:171], v[124:127]
	v_mfma_f32_16x16x32_bf16 v[120:123], v[156:159], v[168:171], v[120:123]
	v_mfma_f32_16x16x32_bf16 v[116:119], v[160:163], v[168:171], v[116:119]
	v_mfma_f32_16x16x32_bf16 v[112:115], v[164:167], v[168:171], v[112:115]
	s_waitcnt lgkmcnt(6)
	v_mfma_f32_16x16x32_bf16 v[108:111], v[134:137], v[172:175], v[108:111]
	v_mfma_f32_16x16x32_bf16 v[104:107], v[156:159], v[172:175], v[104:107]
	v_mfma_f32_16x16x32_bf16 v[100:103], v[160:163], v[172:175], v[100:103]
	v_mfma_f32_16x16x32_bf16 v[96:99], v[164:167], v[172:175], v[96:99]
	s_waitcnt lgkmcnt(5)
	v_mfma_f32_16x16x32_bf16 v[92:95], v[134:137], v[176:179], v[92:95]
	v_mfma_f32_16x16x32_bf16 v[88:91], v[156:159], v[176:179], v[88:91]
	v_mfma_f32_16x16x32_bf16 v[84:87], v[160:163], v[176:179], v[84:87]
	v_mfma_f32_16x16x32_bf16 v[80:83], v[164:167], v[176:179], v[80:83]
	s_waitcnt lgkmcnt(4)
	v_mfma_f32_16x16x32_bf16 v[76:79], v[134:137], v[180:183], v[76:79]
	v_mfma_f32_16x16x32_bf16 v[72:75], v[156:159], v[180:183], v[72:75]
	v_mfma_f32_16x16x32_bf16 v[68:71], v[160:163], v[180:183], v[68:71]
	v_mfma_f32_16x16x32_bf16 v[64:67], v[164:167], v[180:183], v[64:67]
	s_waitcnt lgkmcnt(3)
	s_nop 0
	v_mfma_f32_16x16x32_bf16 v[60:63], v[134:137], v[184:187], v[60:63]
	v_mfma_f32_16x16x32_bf16 v[56:59], v[156:159], v[184:187], v[56:59]
	v_mfma_f32_16x16x32_bf16 v[52:55], v[160:163], v[184:187], v[52:55]
	v_mfma_f32_16x16x32_bf16 v[48:51], v[164:167], v[184:187], v[48:51]
	s_waitcnt lgkmcnt(2)
	v_mfma_f32_16x16x32_bf16 v[44:47], v[134:137], v[188:191], v[44:47]
	v_mfma_f32_16x16x32_bf16 v[40:43], v[156:159], v[188:191], v[40:43]
	v_mfma_f32_16x16x32_bf16 v[36:39], v[160:163], v[188:191], v[36:39]
	v_mfma_f32_16x16x32_bf16 v[28:31], v[164:167], v[188:191], v[28:31]
	s_waitcnt lgkmcnt(1)
	v_mfma_f32_16x16x32_bf16 v[16:19], v[134:137], v[192:195], v[16:19]
	v_mfma_f32_16x16x32_bf16 v[8:11], v[156:159], v[192:195], v[8:11]
	v_mfma_f32_16x16x32_bf16 v[4:7], v[160:163], v[192:195], v[4:7]
	v_mfma_f32_16x16x32_bf16 v[0:3], v[164:167], v[192:195], v[0:3]
	s_waitcnt lgkmcnt(0)
	v_mfma_f32_16x16x32_bf16 v[32:35], v[134:137], v[200:203], v[32:35]
	v_mfma_f32_16x16x32_bf16 v[24:27], v[156:159], v[200:203], v[24:27]
	v_mfma_f32_16x16x32_bf16 v[20:23], v[160:163], v[200:203], v[20:23]
	v_mfma_f32_16x16x32_bf16 v[12:15], v[164:167], v[200:203], v[12:15]
	s_setprio 0
	s_and_b64 vcc, exec, s[52:53]
	s_cbranch_vccnz .Lgt4_last
	s_add_i32 s36, s43, 1
	s_cmp_lg_u32 s43, 2
	s_cselect_b32 s43, s36, 0
	s_add_i32 s36, s41, 1
	s_cmp_lg_u32 s41, 2
	s_cselect_b32 s41, s36, 0
	s_add_i32 s35, s35, 1
	s_add_u32 s48, s48, 0x2000
	s_addc_u32 s49, s49, 0
	s_add_u32 s50, s50, 0x4000
	s_addc_u32 s51, s51, 0
	s_cmp_eq_u32 s35, 32
	s_waitcnt vmcnt(6)
	s_barrier
	s_branch .LBB0_1354

; template <int EPI>
; __device__ __forceinline__ void gemm_phase(const u16* __restrict__ A0, int nksA, size_t sA, const u16* __restrict__ B0, int nksB, size_t sB,
;                                            int K, int nM, int nN, int nbatch, const EpiArgs ea, char* smem, int bid, int nblk) {
;     ...
;     for (int kk = 0; kk < nk; ++kk) {
;       const bool more = kk + 2 < nk;
;       if (more) GSTAGE(kk + 2, nbuf);
;       bf16x8 Bl[4], At[8];
;       {
;         const int bb = sb0 + buf * 8192, ab = sa0 + buf * 16384;
;         asm volatile(
;             "ds_read_b128 %0, %12\n\tds_read_b128 %1, %12 offset:1024\n\tds_read_b128 %2, %12 offset:2048\n\tds_read_b128 %3, %12 offset:3072\n\t"
;             "ds_read_b128 %4, %13\n\tds_read_b128 %5, %13 offset:1024\n\tds_read_b128 %6, %13 offset:2048\n\tds_read_b128 %7, %13 offset:3072\n\t"
;             "ds_read_b128 %8, %13 offset:4096\n\tds_read_b128 %9, %13 offset:5120\n\tds_read_b128 %10, %13 offset:6144\n\tds_read_b128 %11, %13 offset:7168\n\t"
;             "s_waitcnt lgkmcnt(4)"
;             : "=&v"(Bl[0]), "=&v"(Bl[1]), "=&v"(Bl[2]), "=&v"(Bl[3]), "=&v"(At[0]), "=&v"(At[1]), "=&v"(At[2]), "=&v"(At[3]),
;               "=&v"(At[4]), "=&v"(At[5]), "=&v"(At[6]), "=&v"(At[7])
;             : "v"(bb), "v"(ab)
;             : "memory");
;       }
;       __builtin_amdgcn_s_setprio(1);
; #pragma unroll
;       for (int m = 0; m < 4; ++m)
; #pragma unroll
;         for (int n = 0; n < 4; ++n) acc[m][n] = __builtin_amdgcn_mfma_f32_16x16x32_bf16(Bl[n], At[m], acc[m][n], 0, 0, 0);
;       __builtin_amdgcn_sched_barrier(0);
;       asm volatile("s_waitcnt lgkmcnt(0)" : "+v"(At[4]), "+v"(At[5]), "+v"(At[6]), "+v"(At[7]) :: "memory");
;       __builtin_amdgcn_sched_barrier(0);
; #pragma unroll
;       for (int m = 4; m < 8; ++m)
; #pragma unroll
;         for (int n = 0; n < 4; ++n) acc[m][n] = __builtin_amdgcn_mfma_f32_16x16x32_bf16(Bl[n], At[m], acc[m][n], 0, 0, 0);
;       __builtin_amdgcn_s_setprio(0);
;       if (more) asm volatile("s_waitcnt vmcnt(6)\n\ts_barrier" ::: "memory");
;       else asm volatile("s_waitcnt vmcnt(0)\n\ts_barrier" ::: "memory");
;       buf = (buf == 2) ? 0 : buf + 1; nbuf = (nbuf == 2) ? 0 : nbuf + 1;
;     }
.LBB0_1501:
	v_lshl_add_u32 v139, s58, 13, v145
	v_lshl_add_u32 v140, s58, 14, v143
	ds_read_b128 v[158:161], v139
	ds_read_b128 v[162:165], v139 offset:1024
	ds_read_b128 v[166:169], v139 offset:2048
	ds_read_b128 v[170:173], v139 offset:3072
	ds_read_b128 v[174:177], v140
	ds_read_b128 v[178:181], v140 offset:1024
	ds_read_b128 v[182:185], v140 offset:2048
	ds_read_b128 v[186:189], v140 offset:3072
	ds_read_b128 v[190:193], v140 offset:4096
	ds_read_b128 v[194:197], v140 offset:5120
	ds_read_b128 v[200:203], v140 offset:6144
	ds_read_b128 v[204:207], v140 offset:7168
	s_waitcnt lgkmcnt(7)
	s_setprio 1
	v_mfma_f32_16x16x32_bf16 v[124:127], v[158:161], v[174:177], v[124:127]
	v_mfma_f32_16x16x32_bf16 v[120:123], v[162:165], v[174:177], v[120:123]
	v_mfma_f32_16x16x32_bf16 v[116:119], v[166:169], v[174:177], v[116:119]
	v_mfma_f32_16x16x32_bf16 v[112:115], v[170:173], v[174:177], v[112:115]
	s_waitcnt lgkmcnt(6)
	v_mfma_f32_16x16x32_bf16 v[108:111], v[158:161], v[178:181], v[108:111]
	v_mfma_f32_16x16x32_bf16 v[104:107], v[162:165], v[178:181], v[104:107]
	v_mfma_f32_16x16x32_bf16 v[100:103], v[166:169], v[178:181], v[100:103]
	v_mfma_f32_16x16x32_bf16 v[96:99], v[170:173], v[178:181], v[96:99]
	s_waitcnt lgkmcnt(5)
	v_mfma_f32_16x16x32_bf16 v[92:95], v[158:161], v[182:185], v[92:95]
	v_mfma_f32_16x16x32_bf16 v[88:91], v[162:165], v[182:185], v[88:91]
	v_mfma_f32_16x16x32_bf16 v[84:87], v[166:169], v[182:185], v[84:87]
	v_mfma_f32_16x16x32_bf16 v[80:83], v[170:173], v[182:185], v[80:83]
	s_waitcnt lgkmcnt(4)
	v_mfma_f32_16x16x32_bf16 v[76:79], v[158:161], v[186:189], v[76:79]
	v_mfma_f32_16x16x32_bf16 v[72:75], v[162:165], v[186:189], v[72:75]
	v_mfma_f32_16x16x32_bf16 v[68:71], v[166:169], v[186:189], v[68:71]
	v_mfma_f32_16x16x32_bf16 v[64:67], v[170:173], v[186:189], v[64:67]
	s_waitcnt lgkmcnt(3)
	s_nop 0
	v_mfma_f32_16x16x32_bf16 v[60:63], v[158:161], v[190:193], v[60:63]
	v_mfma_f32_16x16x32_bf16 v[56:59], v[162:165], v[190:193], v[56:59]
	v_mfma_f32_16x16x32_bf16 v[52:55], v[166:169], v[190:193], v[52:55]
	v_mfma_f32_16x16x32_bf16 v[48:51], v[170:173], v[190:193], v[48:51]
	s_waitcnt lgkmcnt(2)
	v_mfma_f32_16x16x32_bf16 v[44:47], v[158:161], v[194:197], v[44:47]
	v_mfma_f32_16x16x32_bf16 v[40:43], v[162:165], v[194:197], v[40:43]
	v_mfma_f32_16x16x32_bf16 v[36:39], v[166:169], v[194:197], v[36:39]
	v_mfma_f32_16x16x32_bf16 v[32:35], v[170:173], v[194:197], v[32:35]
	s_waitcnt lgkmcnt(1)
	v_mfma_f32_16x16x32_bf16 v[20:23], v[158:161], v[200:203], v[20:23]
	v_mfma_f32_16x16x32_bf16 v[16:19], v[162:165], v[200:203], v[16:19]
	v_mfma_f32_16x16x32_bf16 v[4:7], v[166:169], v[200:203], v[4:7]
	v_mfma_f32_16x16x32_bf16 v[0:3], v[170:173], v[200:203], v[0:3]
	s_waitcnt lgkmcnt(0)
	v_mfma_f32_16x16x32_bf16 v[24:27], v[158:161], v[204:207], v[24:27]
	v_mfma_f32_16x16x32_bf16 v[28:31], v[162:165], v[204:207], v[28:31]
	v_mfma_f32_16x16x32_bf16 v[8:11], v[166:169], v[204:207], v[8:11]
	v_mfma_f32_16x16x32_bf16 v[12:15], v[170:173], v[204:207], v[12:15]
	s_setprio 0
	s_and_b64 vcc, exec, s[52:53]
	s_cbranch_vccnz .Lgt5_last
	s_add_i32 s44, s58, 1
	s_cmp_lg_u32 s58, 2
	s_cselect_b32 s58, s44, 0
	s_add_i32 s44, s43, 1
	s_cmp_lg_u32 s43, 2
	s_cselect_b32 s43, s44, 0
	s_add_i32 s41, s41, 1
	s_add_u32 s48, s48, 0x2000
	s_addc_u32 s49, s49, 0
	s_add_u32 s50, s50, 0x4000
	s_addc_u32 s51, s51, 0
	s_cmp_eq_u32 s41, 32
	s_waitcnt vmcnt(6)
	s_barrier
	s_branch .LBB0_1499

; template <int EPI>
; __device__ __forceinline__ void gemm_phase(const u16* __restrict__ A0, int nksA, size_t sA, const u16* __restrict__ B0, int nksB, size_t sB,
;                                            int K, int nM, int nN, int nbatch, const EpiArgs ea, char* smem, int bid, int nblk) {
;     ...
;     for (int kk = 0; kk < nk; ++kk) {
;       const bool more = kk + 2 < nk;
;       if (more) GSTAGE(kk + 2, nbuf);
;       bf16x8 Bl[4], At[8];
;       {
;         const int bb = sb0 + buf * 8192, ab = sa0 + buf * 16384;
;         asm volatile(
;             "ds_read_b128 %0, %12\n\tds_read_b128 %1, %12 offset:1024\n\tds_read_b128 %2, %12 offset:2048\n\tds_read_b128 %3, %12 offset:3072\n\t"
;             "ds_read_b128 %4, %13\n\tds_read_b128 %5, %13 offset:1024\n\tds_read_b128 %6, %13 offset:2048\n\tds_read_b128 %7, %13 offset:3072\n\t"
;             "ds_read_b128 %8, %13 offset:4096\n\tds_read_b128 %9, %13 offset:5120\n\tds_read_b128 %10, %13 offset:6144\n\tds_read_b128 %11, %13 offset:7168\n\t"
;             "s_waitcnt lgkmcnt(4)"
;             : "=&v"(Bl[0]), "=&v"(Bl[1]), "=&v"(Bl[2]), "=&v"(Bl[3]), "=&v"(At[0]), "=&v"(At[1]), "=&v"(At[2]), "=&v"(At[3]),
;               "=&v"(At[4]), "=&v"(At[5]), "=&v"(At[6]), "=&v"(At[7])
;             : "v"(bb), "v"(ab)
;             : "memory");
;       }
;       __builtin_amdgcn_s_setprio(1);
; #pragma unroll
;       for (int m = 0; m < 4; ++m)
; #pragma unroll
;         for (int n = 0; n < 4; ++n) acc[m][n] = __builtin_amdgcn_mfma_f32_16x16x32_bf16(Bl[n], At[m], acc[m][n], 0, 0, 0);
;       __builtin_amdgcn_sched_barrier(0);
;       asm volatile("s_waitcnt lgkmcnt(0)" : "+v"(At[4]), "+v"(At[5]), "+v"(At[6]), "+v"(At[7]) :: "memory");
;       __builtin_amdgcn_sched_barrier(0);
; #pragma unroll
;       for (int m = 4; m < 8; ++m)
; #pragma unroll
;         for (int n = 0; n < 4; ++n) acc[m][n] = __builtin_amdgcn_mfma_f32_16x16x32_bf16(Bl[n], At[m], acc[m][n], 0, 0, 0);
;       __builtin_amdgcn_s_setprio(0);
;       if (more) asm volatile("s_waitcnt vmcnt(6)\n\ts_barrier" ::: "memory");
;       else asm volatile("s_waitcnt vmcnt(0)\n\ts_barrier" ::: "memory");
;       buf = (buf == 2) ? 0 : buf + 1; nbuf = (nbuf == 2) ? 0 : nbuf + 1;
;     }
.LBB0_1574:
	v_lshl_add_u32 v138, s53, 13, v143
	v_lshl_add_u32 v139, s53, 14, v142
	ds_read_b128 v[134:137], v138
	ds_read_b128 v[156:159], v138 offset:1024
	ds_read_b128 v[160:163], v138 offset:2048
	ds_read_b128 v[164:167], v138 offset:3072
	ds_read_b128 v[168:171], v139
	ds_read_b128 v[172:175], v139 offset:1024
	ds_read_b128 v[176:179], v139 offset:2048
	ds_read_b128 v[180:183], v139 offset:3072
	ds_read_b128 v[184:187], v139 offset:4096
	ds_read_b128 v[188:191], v139 offset:5120
	ds_read_b128 v[192:195], v139 offset:6144
	ds_read_b128 v[200:203], v139 offset:7168
	s_waitcnt lgkmcnt(7)
	s_setprio 1
	v_mfma_f32_16x16x32_bf16 v[124:127], v[134:137], v[168:171], v[124:127]
	v_mfma_f32_16x16x32_bf16 v[120:123], v[156:159], v[168:171], v[120:123]
	v_mfma_f32_16x16x32_bf16 v[116:119], v[160:163], v[168:171], v[116:119]
	v_mfma_f32_16x16x32_bf16 v[112:115], v[164:167], v[168:171], v[112:115]
	s_waitcnt lgkmcnt(6)
	v_mfma_f32_16x16x32_bf16 v[108:111], v[134:137], v[172:175], v[108:111]
	v_mfma_f32_16x16x32_bf16 v[104:107], v[156:159], v[172:175], v[104:107]
	v_mfma_f32_16x16x32_bf16 v[100:103], v[160:163], v[172:175], v[100:103]
	v_mfma_f32_16x16x32_bf16 v[96:99], v[164:167], v[172:175], v[96:99]
	s_waitcnt lgkmcnt(5)
	v_mfma_f32_16x16x32_bf16 v[92:95], v[134:137], v[176:179], v[92:95]
	v_mfma_f32_16x16x32_bf16 v[88:91], v[156:159], v[176:179], v[88:91]
	v_mfma_f32_16x16x32_bf16 v[84:87], v[160:163], v[176:179], v[84:87]
	v_mfma_f32_16x16x32_bf16 v[80:83], v[164:167], v[176:179], v[80:83]
	s_waitcnt lgkmcnt(4)
	v_mfma_f32_16x16x32_bf16 v[76:79], v[134:137], v[180:183], v[76:79]
	v_mfma_f32_16x16x32_bf16 v[72:75], v[156:159], v[180:183], v[72:75]
	v_mfma_f32_16x16x32_bf16 v[68:71], v[160:163], v[180:183], v[68:71]
	v_mfma_f32_16x16x32_bf16 v[64:67], v[164:167], v[180:183], v[64:67]
	s_waitcnt lgkmcnt(3)
	s_nop 0
	v_mfma_f32_16x16x32_bf16 v[60:63], v[134:137], v[184:187], v[60:63]
	v_mfma_f32_16x16x32_bf16 v[56:59], v[156:159], v[184:187], v[56:59]
	v_mfma_f32_16x16x32_bf16 v[52:55], v[160:163], v[184:187], v[52:55]
	v_mfma_f32_16x16x32_bf16 v[48:51], v[164:167], v[184:187], v[48:51]
	s_waitcnt lgkmcnt(2)
	v_mfma_f32_16x16x32_bf16 v[44:47], v[134:137], v[188:191], v[44:47]
	v_mfma_f32_16x16x32_bf16 v[40:43], v[156:159], v[188:191], v[40:43]
	v_mfma_f32_16x16x32_bf16 v[36:39], v[160:163], v[188:191], v[36:39]
	v_mfma_f32_16x16x32_bf16 v[32:35], v[164:167], v[188:191], v[32:35]
	s_waitcnt lgkmcnt(1)
	v_mfma_f32_16x16x32_bf16 v[20:23], v[134:137], v[192:195], v[20:23]
	v_mfma_f32_16x16x32_bf16 v[8:11], v[156:159], v[192:195], v[8:11]
	v_mfma_f32_16x16x32_bf16 v[4:7], v[160:163], v[192:195], v[4:7]
	v_mfma_f32_16x16x32_bf16 v[0:3], v[164:167], v[192:195], v[0:3]
	s_waitcnt lgkmcnt(0)
	v_mfma_f32_16x16x32_bf16 v[28:31], v[134:137], v[200:203], v[28:31]
	v_mfma_f32_16x16x32_bf16 v[24:27], v[156:159], v[200:203], v[24:27]
	v_mfma_f32_16x16x32_bf16 v[16:19], v[160:163], v[200:203], v[16:19]
	v_mfma_f32_16x16x32_bf16 v[12:15], v[164:167], v[200:203], v[12:15]
	s_setprio 0
	s_and_b64 vcc, exec, s[40:41]
	s_cbranch_vccnz .Lgt6_last
	s_add_i32 s40, s53, 1
	s_cmp_lg_u32 s53, 2
	s_cselect_b32 s53, s40, 0
	s_add_i32 s40, s52, 1
	s_cmp_lg_u32 s52, 2
	s_cselect_b32 s52, s40, 0
	s_add_i32 s51, s51, 1
	s_add_u32 s36, s36, 0x2000
	s_addc_u32 s37, s37, 0
	s_add_u32 s38, s38, 0x4000
	s_addc_u32 s39, s39, 0
	s_cmpk_eq_i32 s51, 0x58
	s_waitcnt vmcnt(6)
	s_barrier
	s_branch .LBB0_1572

; template <int EPI>
; __device__ __forceinline__ void gemm_phase(const u16* __restrict__ A0, int nksA, size_t sA, const u16* __restrict__ B0, int nksB, size_t sB,
;                                            int K, int nM, int nN, int nbatch, const EpiArgs ea, char* smem, int bid, int nblk) {
;     ...
;     for (int kk = 0; kk < nk; ++kk) {
;       const bool more = kk + 2 < nk;
;       if (more) GSTAGE(kk + 2, nbuf);
;       bf16x8 Bl[4], At[8];
;       {
;         const int bb = sb0 + buf * 8192, ab = sa0 + buf * 16384;
;         asm volatile(
;             "ds_read_b128 %0, %12\n\tds_read_b128 %1, %12 offset:1024\n\tds_read_b128 %2, %12 offset:2048\n\tds_read_b128 %3, %12 offset:3072\n\t"
;             "ds_read_b128 %4, %13\n\tds_read_b128 %5, %13 offset:1024\n\tds_read_b128 %6, %13 offset:2048\n\tds_read_b128 %7, %13 offset:3072\n\t"
;             "ds_read_b128 %8, %13 offset:4096\n\tds_read_b128 %9, %13 offset:5120\n\tds_read_b128 %10, %13 offset:6144\n\tds_read_b128 %11, %13 offset:7168\n\t"
;             "s_waitcnt lgkmcnt(4)"
;             : "=&v"(Bl[0]), "=&v"(Bl[1]), "=&v"(Bl[2]), "=&v"(Bl[3]), "=&v"(At[0]), "=&v"(At[1]), "=&v"(At[2]), "=&v"(At[3]),
;               "=&v"(At[4]), "=&v"(At[5]), "=&v"(At[6]), "=&v"(At[7])
;             : "v"(bb), "v"(ab)
;             : "memory");
;       }
;       __builtin_amdgcn_s_setprio(1);
; #pragma unroll
;       for (int m = 0; m < 4; ++m)
; #pragma unroll
;         for (int n = 0; n < 4; ++n) acc[m][n] = __builtin_amdgcn_mfma_f32_16x16x32_bf16(Bl[n], At[m], acc[m][n], 0, 0, 0);
;       __builtin_amdgcn_sched_barrier(0);
;       asm volatile("s_waitcnt lgkmcnt(0)" : "+v"(At[4]), "+v"(At[5]), "+v"(At[6]), "+v"(At[7]) :: "memory");
;       __builtin_amdgcn_sched_barrier(0);
; #pragma unroll
;       for (int m = 4; m < 8; ++m)
; #pragma unroll
;         for (int n = 0; n < 4; ++n) acc[m][n] = __builtin_amdgcn_mfma_f32_16x16x32_bf16(Bl[n], At[m], acc[m][n], 0, 0, 0);
;       __builtin_amdgcn_s_setprio(0);
;       if (more) asm volatile("s_waitcnt vmcnt(6)\n\ts_barrier" ::: "memory");
;       else asm volatile("s_waitcnt vmcnt(0)\n\ts_barrier" ::: "memory");
;       buf = (buf == 2) ? 0 : buf + 1; nbuf = (nbuf == 2) ? 0 : nbuf + 1;
;     }
.LBB0_1719:
	v_lshl_add_u32 v149, s52, 13, v135
	v_lshl_add_u32 v199, s52, 14, v134
	ds_read_b128 v[150:153], v149
	ds_read_b128 v[154:157], v149 offset:1024
	ds_read_b128 v[158:161], v149 offset:2048
	ds_read_b128 v[162:165], v149 offset:3072
	ds_read_b128 v[166:169], v199
	ds_read_b128 v[170:173], v199 offset:1024
	ds_read_b128 v[174:177], v199 offset:2048
	ds_read_b128 v[178:181], v199 offset:3072
	ds_read_b128 v[182:185], v199 offset:4096
	ds_read_b128 v[186:189], v199 offset:5120
	ds_read_b128 v[190:193], v199 offset:6144
	ds_read_b128 v[194:197], v199 offset:7168
	s_waitcnt lgkmcnt(7)
	s_setprio 1
	v_mfma_f32_16x16x32_bf16 v[124:127], v[150:153], v[166:169], v[124:127]
	v_mfma_f32_16x16x32_bf16 v[120:123], v[154:157], v[166:169], v[120:123]
	v_mfma_f32_16x16x32_bf16 v[116:119], v[158:161], v[166:169], v[116:119]
	v_mfma_f32_16x16x32_bf16 v[112:115], v[162:165], v[166:169], v[112:115]
	s_waitcnt lgkmcnt(6)
	v_mfma_f32_16x16x32_bf16 v[108:111], v[150:153], v[170:173], v[108:111]
	v_mfma_f32_16x16x32_bf16 v[104:107], v[154:157], v[170:173], v[104:107]
	v_mfma_f32_16x16x32_bf16 v[100:103], v[158:161], v[170:173], v[100:103]
	v_mfma_f32_16x16x32_bf16 v[96:99], v[162:165], v[170:173], v[96:99]
	s_waitcnt lgkmcnt(5)
	v_mfma_f32_16x16x32_bf16 v[92:95], v[150:153], v[174:177], v[92:95]
	v_mfma_f32_16x16x32_bf16 v[88:91], v[154:157], v[174:177], v[88:91]
	v_mfma_f32_16x16x32_bf16 v[84:87], v[158:161], v[174:177], v[84:87]
	v_mfma_f32_16x16x32_bf16 v[80:83], v[162:165], v[174:177], v[80:83]
	s_waitcnt lgkmcnt(4)
	v_mfma_f32_16x16x32_bf16 v[76:79], v[150:153], v[178:181], v[76:79]
	v_mfma_f32_16x16x32_bf16 v[72:75], v[154:157], v[178:181], v[72:75]
	v_mfma_f32_16x16x32_bf16 v[68:71], v[158:161], v[178:181], v[68:71]
	v_mfma_f32_16x16x32_bf16 v[64:67], v[162:165], v[178:181], v[64:67]
	s_waitcnt lgkmcnt(3)
	s_nop 0
	v_mfma_f32_16x16x32_bf16 v[60:63], v[150:153], v[182:185], v[60:63]
	v_mfma_f32_16x16x32_bf16 v[40:43], v[154:157], v[182:185], v[40:43]
	v_mfma_f32_16x16x32_bf16 v[36:39], v[158:161], v[182:185], v[36:39]
	v_mfma_f32_16x16x32_bf16 v[32:35], v[162:165], v[182:185], v[32:35]
	s_waitcnt lgkmcnt(2)
	v_mfma_f32_16x16x32_bf16 v[28:31], v[150:153], v[186:189], v[28:31]
	v_mfma_f32_16x16x32_bf16 v[24:27], v[154:157], v[186:189], v[24:27]
	v_mfma_f32_16x16x32_bf16 v[20:23], v[158:161], v[186:189], v[20:23]
	v_mfma_f32_16x16x32_bf16 v[16:19], v[162:165], v[186:189], v[16:19]
	s_waitcnt lgkmcnt(1)
	v_mfma_f32_16x16x32_bf16 v[12:15], v[150:153], v[190:193], v[12:15]
	v_mfma_f32_16x16x32_bf16 v[8:11], v[154:157], v[190:193], v[8:11]
	v_mfma_f32_16x16x32_bf16 v[4:7], v[158:161], v[190:193], v[4:7]
	v_mfma_f32_16x16x32_bf16 v[0:3], v[162:165], v[190:193], v[0:3]
	s_waitcnt lgkmcnt(0)
	v_mfma_f32_16x16x32_bf16 v[56:59], v[150:153], v[194:197], v[56:59]
	v_mfma_f32_16x16x32_bf16 v[52:55], v[154:157], v[194:197], v[52:55]
	v_mfma_f32_16x16x32_bf16 v[48:51], v[158:161], v[194:197], v[48:51]
	v_mfma_f32_16x16x32_bf16 v[44:47], v[162:165], v[194:197], v[44:47]
	s_setprio 0
	s_and_b64 vcc, exec, s[44:45]
	s_cbranch_vccnz .Lgt7_last
	s_add_i32 s44, s52, 1
	s_cmp_lg_u32 s52, 2
	s_cselect_b32 s52, s44, 0
	s_add_i32 s44, s39, 1
	s_cmp_lg_u32 s39, 2
	s_cselect_b32 s39, s44, 0
	s_add_i32 s37, s37, 1
	s_add_u32 s40, s40, 0x2000
	s_addc_u32 s41, s41, 0
	s_add_u32 s42, s42, 0x4000
	s_addc_u32 s43, s43, 0
	s_cmp_eq_u32 s37, 32
	s_waitcnt vmcnt(6)
	s_barrier
	s_branch .LBB0_1717

; template <int EPI>
; __device__ __forceinline__ void gemm_phase(const u16* __restrict__ A0, int nksA, size_t sA, const u16* __restrict__ B0, int nksB, size_t sB,
;                                            int K, int nM, int nN, int nbatch, const EpiArgs ea, char* smem, int bid, int nblk) {
;     ...
;     for (int kk = 0; kk < nk; ++kk) {
;       const bool more = kk + 2 < nk;
;       if (more) GSTAGE(kk + 2, nbuf);
;       bf16x8 Bl[4], At[8];
;       {
;         const int bb = sb0 + buf * 8192, ab = sa0 + buf * 16384;
;         asm volatile(
;             "ds_read_b128 %0, %12\n\tds_read_b128 %1, %12 offset:1024\n\tds_read_b128 %2, %12 offset:2048\n\tds_read_b128 %3, %12 offset:3072\n\t"
;             "ds_read_b128 %4, %13\n\tds_read_b128 %5, %13 offset:1024\n\tds_read_b128 %6, %13 offset:2048\n\tds_read_b128 %7, %13 offset:3072\n\t"
;             "ds_read_b128 %8, %13 offset:4096\n\tds_read_b128 %9, %13 offset:5120\n\tds_read_b128 %10, %13 offset:6144\n\tds_read_b128 %11, %13 offset:7168\n\t"
;             "s_waitcnt lgkmcnt(4)"
;             : "=&v"(Bl[0]), "=&v"(Bl[1]), "=&v"(Bl[2]), "=&v"(Bl[3]), "=&v"(At[0]), "=&v"(At[1]), "=&v"(At[2]), "=&v"(At[3]),
;               "=&v"(At[4]), "=&v"(At[5]), "=&v"(At[6]), "=&v"(At[7])
;             : "v"(bb), "v"(ab)
;             : "memory");
;       }
;       __builtin_amdgcn_s_setprio(1);
; #pragma unroll
;       for (int m = 0; m < 4; ++m)
; #pragma unroll
;         for (int n = 0; n < 4; ++n) acc[m][n] = __builtin_amdgcn_mfma_f32_16x16x32_bf16(Bl[n], At[m], acc[m][n], 0, 0, 0);
;       __builtin_amdgcn_sched_barrier(0);
;       asm volatile("s_waitcnt lgkmcnt(0)" : "+v"(At[4]), "+v"(At[5]), "+v"(At[6]), "+v"(At[7]) :: "memory");
;       __builtin_amdgcn_sched_barrier(0);
; #pragma unroll
;       for (int m = 4; m < 8; ++m)
; #pragma unroll
;         for (int n = 0; n < 4; ++n) acc[m][n] = __builtin_amdgcn_mfma_f32_16x16x32_bf16(Bl[n], At[m], acc[m][n], 0, 0, 0);
;       __builtin_amdgcn_s_setprio(0);
;       if (more) asm volatile("s_waitcnt vmcnt(6)\n\ts_barrier" ::: "memory");
;       else asm volatile("s_waitcnt vmcnt(0)\n\ts_barrier" ::: "memory");
;       buf = (buf == 2) ? 0 : buf + 1; nbuf = (nbuf == 2) ? 0 : nbuf + 1;
;     }
.LBB0_1873:
	v_lshl_add_u32 v138, s51, 13, v143
	v_lshl_add_u32 v139, s51, 14, v142
	ds_read_b128 v[134:137], v138
	ds_read_b128 v[156:159], v138 offset:1024
	ds_read_b128 v[160:163], v138 offset:2048
	ds_read_b128 v[164:167], v138 offset:3072
	ds_read_b128 v[168:171], v139
	ds_read_b128 v[172:175], v139 offset:1024
	ds_read_b128 v[176:179], v139 offset:2048
	ds_read_b128 v[180:183], v139 offset:3072
	ds_read_b128 v[184:187], v139 offset:4096
	ds_read_b128 v[188:191], v139 offset:5120
	ds_read_b128 v[192:195], v139 offset:6144
	ds_read_b128 v[200:203], v139 offset:7168
	s_waitcnt lgkmcnt(7)
	s_setprio 1
	v_mfma_f32_16x16x32_bf16 v[124:127], v[134:137], v[168:171], v[124:127]
	v_mfma_f32_16x16x32_bf16 v[120:123], v[156:159], v[168:171], v[120:123]
	v_mfma_f32_16x16x32_bf16 v[116:119], v[160:163], v[168:171], v[116:119]
	v_mfma_f32_16x16x32_bf16 v[112:115], v[164:167], v[168:171], v[112:115]
	s_waitcnt lgkmcnt(6)
	v_mfma_f32_16x16x32_bf16 v[108:111], v[134:137], v[172:175], v[108:111]
	v_mfma_f32_16x16x32_bf16 v[104:107], v[156:159], v[172:175], v[104:107]
	v_mfma_f32_16x16x32_bf16 v[100:103], v[160:163], v[172:175], v[100:103]
	v_mfma_f32_16x16x32_bf16 v[96:99], v[164:167], v[172:175], v[96:99]
	s_waitcnt lgkmcnt(5)
	v_mfma_f32_16x16x32_bf16 v[92:95], v[134:137], v[176:179], v[92:95]
	v_mfma_f32_16x16x32_bf16 v[88:91], v[156:159], v[176:179], v[88:91]
	v_mfma_f32_16x16x32_bf16 v[84:87], v[160:163], v[176:179], v[84:87]
	v_mfma_f32_16x16x32_bf16 v[80:83], v[164:167], v[176:179], v[80:83]
	s_waitcnt lgkmcnt(4)
	v_mfma_f32_16x16x32_bf16 v[76:79], v[134:137], v[180:183], v[76:79]
	v_mfma_f32_16x16x32_bf16 v[72:75], v[156:159], v[180:183], v[72:75]
	v_mfma_f32_16x16x32_bf16 v[68:71], v[160:163], v[180:183], v[68:71]
	v_mfma_f32_16x16x32_bf16 v[64:67], v[164:167], v[180:183], v[64:67]
	s_waitcnt lgkmcnt(3)
	s_nop 0
	v_mfma_f32_16x16x32_bf16 v[60:63], v[134:137], v[184:187], v[60:63]
	v_mfma_f32_16x16x32_bf16 v[56:59], v[156:159], v[184:187], v[56:59]
	v_mfma_f32_16x16x32_bf16 v[52:55], v[160:163], v[184:187], v[52:55]
	v_mfma_f32_16x16x32_bf16 v[48:51], v[164:167], v[184:187], v[48:51]
	s_waitcnt lgkmcnt(2)
	v_mfma_f32_16x16x32_bf16 v[44:47], v[134:137], v[188:191], v[44:47]
	v_mfma_f32_16x16x32_bf16 v[40:43], v[156:159], v[188:191], v[40:43]
	v_mfma_f32_16x16x32_bf16 v[36:39], v[160:163], v[188:191], v[36:39]
	v_mfma_f32_16x16x32_bf16 v[32:35], v[164:167], v[188:191], v[32:35]
	s_waitcnt lgkmcnt(1)
	v_mfma_f32_16x16x32_bf16 v[20:23], v[134:137], v[192:195], v[20:23]
	v_mfma_f32_16x16x32_bf16 v[8:11], v[156:159], v[192:195], v[8:11]
	v_mfma_f32_16x16x32_bf16 v[4:7], v[160:163], v[192:195], v[4:7]
	v_mfma_f32_16x16x32_bf16 v[0:3], v[164:167], v[192:195], v[0:3]
	s_waitcnt lgkmcnt(0)
	v_mfma_f32_16x16x32_bf16 v[28:31], v[134:137], v[200:203], v[28:31]
	v_mfma_f32_16x16x32_bf16 v[24:27], v[156:159], v[200:203], v[24:27]
	v_mfma_f32_16x16x32_bf16 v[16:19], v[160:163], v[200:203], v[16:19]
	v_mfma_f32_16x16x32_bf16 v[12:15], v[164:167], v[200:203], v[12:15]
	s_setprio 0
	s_and_b64 vcc, exec, s[44:45]
	s_cbranch_vccnz .Lgt8_last
	s_add_i32 s44, s51, 1
	s_cmp_lg_u32 s51, 2
	s_cselect_b32 s51, s44, 0
	s_add_i32 s44, s39, 1
	s_cmp_lg_u32 s39, 2
	s_cselect_b32 s39, s44, 0
	s_add_i32 s37, s37, 1
	s_add_u32 s40, s40, 0x2000
	s_addc_u32 s41, s41, 0
	s_add_u32 s42, s42, 0x4000
	s_addc_u32 s43, s43, 0
	s_cmp_eq_u32 s37, 32
	s_waitcnt vmcnt(6)
	s_barrier
	s_branch .LBB0_1871

; template <int EPI>
; __device__ __forceinline__ void gemm_phase(const u16* __restrict__ A0, int nksA, size_t sA, const u16* __restrict__ B0, int nksB, size_t sB,
;                                            int K, int nM, int nN, int nbatch, const EpiArgs ea, char* smem, int bid, int nblk) {
;     ...
;     for (int kk = 0; kk < nk; ++kk) {
;       const bool more = kk + 2 < nk;
;       if (more) GSTAGE(kk + 2, nbuf);
;       bf16x8 Bl[4], At[8];
;       {
;         const int bb = sb0 + buf * 8192, ab = sa0 + buf * 16384;
;         asm volatile(
;             "ds_read_b128 %0, %12\n\tds_read_b128 %1, %12 offset:1024\n\tds_read_b128 %2, %12 offset:2048\n\tds_read_b128 %3, %12 offset:3072\n\t"
;             "ds_read_b128 %4, %13\n\tds_read_b128 %5, %13 offset:1024\n\tds_read_b128 %6, %13 offset:2048\n\tds_read_b128 %7, %13 offset:3072\n\t"
;             "ds_read_b128 %8, %13 offset:4096\n\tds_read_b128 %9, %13 offset:5120\n\tds_read_b128 %10, %13 offset:6144\n\tds_read_b128 %11, %13 offset:7168\n\t"
;             "s_waitcnt lgkmcnt(4)"
;             : "=&v"(Bl[0]), "=&v"(Bl[1]), "=&v"(Bl[2]), "=&v"(Bl[3]), "=&v"(At[0]), "=&v"(At[1]), "=&v"(At[2]), "=&v"(At[3]),
;               "=&v"(At[4]), "=&v"(At[5]), "=&v"(At[6]), "=&v"(At[7])
;             : "v"(bb), "v"(ab)
;             : "memory");
;       }
;       __builtin_amdgcn_s_setprio(1);
; #pragma unroll
;       for (int m = 0; m < 4; ++m)
; #pragma unroll
;         for (int n = 0; n < 4; ++n) acc[m][n] = __builtin_amdgcn_mfma_f32_16x16x32_bf16(Bl[n], At[m], acc[m][n], 0, 0, 0);
;       __builtin_amdgcn_sched_barrier(0);
;       asm volatile("s_waitcnt lgkmcnt(0)" : "+v"(At[4]), "+v"(At[5]), "+v"(At[6]), "+v"(At[7]) :: "memory");
;       __builtin_amdgcn_sched_barrier(0);
; #pragma unroll
;       for (int m = 4; m < 8; ++m)
; #pragma unroll
;         for (int n = 0; n < 4; ++n) acc[m][n] = __builtin_amdgcn_mfma_f32_16x16x32_bf16(Bl[n], At[m], acc[m][n], 0, 0, 0);
;       __builtin_amdgcn_s_setprio(0);
;       if (more) asm volatile("s_waitcnt vmcnt(6)\n\ts_barrier" ::: "memory");
;       else asm volatile("s_waitcnt vmcnt(0)\n\ts_barrier" ::: "memory");
;       buf = (buf == 2) ? 0 : buf + 1; nbuf = (nbuf == 2) ? 0 : nbuf + 1;
;     }
.LBB0_2018:
	v_lshl_add_u32 v139, s54, 13, v145
	v_lshl_add_u32 v140, s54, 14, v143
	ds_read_b128 v[158:161], v139
	ds_read_b128 v[162:165], v139 offset:1024
	ds_read_b128 v[166:169], v139 offset:2048
	ds_read_b128 v[170:173], v139 offset:3072
	ds_read_b128 v[174:177], v140
	ds_read_b128 v[178:181], v140 offset:1024
	ds_read_b128 v[182:185], v140 offset:2048
	ds_read_b128 v[186:189], v140 offset:3072
	ds_read_b128 v[190:193], v140 offset:4096
	ds_read_b128 v[194:197], v140 offset:5120
	ds_read_b128 v[200:203], v140 offset:6144
	ds_read_b128 v[204:207], v140 offset:7168
	s_waitcnt lgkmcnt(7)
	s_setprio 1
	v_mfma_f32_16x16x32_bf16 v[124:127], v[158:161], v[174:177], v[124:127]
	v_mfma_f32_16x16x32_bf16 v[120:123], v[162:165], v[174:177], v[120:123]
	v_mfma_f32_16x16x32_bf16 v[116:119], v[166:169], v[174:177], v[116:119]
	v_mfma_f32_16x16x32_bf16 v[112:115], v[170:173], v[174:177], v[112:115]
	s_waitcnt lgkmcnt(6)
	v_mfma_f32_16x16x32_bf16 v[108:111], v[158:161], v[178:181], v[108:111]
	v_mfma_f32_16x16x32_bf16 v[104:107], v[162:165], v[178:181], v[104:107]
	v_mfma_f32_16x16x32_bf16 v[100:103], v[166:169], v[178:181], v[100:103]
	v_mfma_f32_16x16x32_bf16 v[96:99], v[170:173], v[178:181], v[96:99]
	s_waitcnt lgkmcnt(5)
	v_mfma_f32_16x16x32_bf16 v[92:95], v[158:161], v[182:185], v[92:95]
	v_mfma_f32_16x16x32_bf16 v[88:91], v[162:165], v[182:185], v[88:91]
	v_mfma_f32_16x16x32_bf16 v[84:87], v[166:169], v[182:185], v[84:87]
	v_mfma_f32_16x16x32_bf16 v[80:83], v[170:173], v[182:185], v[80:83]
	s_waitcnt lgkmcnt(4)
	v_mfma_f32_16x16x32_bf16 v[76:79], v[158:161], v[186:189], v[76:79]
	v_mfma_f32_16x16x32_bf16 v[72:75], v[162:165], v[186:189], v[72:75]
	v_mfma_f32_16x16x32_bf16 v[68:71], v[166:169], v[186:189], v[68:71]
	v_mfma_f32_16x16x32_bf16 v[64:67], v[170:173], v[186:189], v[64:67]
	s_waitcnt lgkmcnt(3)
	s_nop 0
	v_mfma_f32_16x16x32_bf16 v[60:63], v[158:161], v[190:193], v[60:63]
	v_mfma_f32_16x16x32_bf16 v[56:59], v[162:165], v[190:193], v[56:59]
	v_mfma_f32_16x16x32_bf16 v[52:55], v[166:169], v[190:193], v[52:55]
	v_mfma_f32_16x16x32_bf16 v[48:51], v[170:173], v[190:193], v[48:51]
	s_waitcnt lgkmcnt(2)
	v_mfma_f32_16x16x32_bf16 v[44:47], v[158:161], v[194:197], v[44:47]
	v_mfma_f32_16x16x32_bf16 v[40:43], v[162:165], v[194:197], v[40:43]
	v_mfma_f32_16x16x32_bf16 v[36:39], v[166:169], v[194:197], v[36:39]
	v_mfma_f32_16x16x32_bf16 v[32:35], v[170:173], v[194:197], v[32:35]
	s_waitcnt lgkmcnt(1)
	v_mfma_f32_16x16x32_bf16 v[20:23], v[158:161], v[200:203], v[20:23]
	v_mfma_f32_16x16x32_bf16 v[16:19], v[162:165], v[200:203], v[16:19]
	v_mfma_f32_16x16x32_bf16 v[4:7], v[166:169], v[200:203], v[4:7]
	v_mfma_f32_16x16x32_bf16 v[0:3], v[170:173], v[200:203], v[0:3]
	s_waitcnt lgkmcnt(0)
	v_mfma_f32_16x16x32_bf16 v[24:27], v[158:161], v[204:207], v[24:27]
	v_mfma_f32_16x16x32_bf16 v[28:31], v[162:165], v[204:207], v[28:31]
	v_mfma_f32_16x16x32_bf16 v[8:11], v[166:169], v[204:207], v[8:11]
	v_mfma_f32_16x16x32_bf16 v[12:15], v[170:173], v[204:207], v[12:15]
	s_setprio 0
	s_and_b64 vcc, exec, s[48:49]
	s_cbranch_vccnz .Lgt9_last
	s_add_i32 s48, s54, 1
	s_cmp_lg_u32 s54, 2
	s_cselect_b32 s54, s48, 0
	s_add_i32 s48, s43, 1
	s_cmp_lg_u32 s43, 2
	s_cselect_b32 s43, s48, 0
	s_add_i32 s41, s41, 1
	s_add_u32 s44, s44, 0x2000
	s_addc_u32 s45, s45, 0
	s_add_u32 s46, s46, 0x4000
	s_addc_u32 s47, s47, 0
	s_cmp_eq_u32 s41, 32
	s_waitcnt vmcnt(6)
	s_barrier
	s_branch .LBB0_2016

; template <int EPI>
; __device__ __forceinline__ void gemm_phase(const u16* __restrict__ A0, int nksA, size_t sA, const u16* __restrict__ B0, int nksB, size_t sB,
;                                            int K, int nM, int nN, int nbatch, const EpiArgs ea, char* smem, int bid, int nblk) {
;     ...
;     for (int kk = 0; kk < nk; ++kk) {
;       const bool more = kk + 2 < nk;
;       if (more) GSTAGE(kk + 2, nbuf);
;       bf16x8 Bl[4], At[8];
;       {
;         const int bb = sb0 + buf * 8192, ab = sa0 + buf * 16384;
;         asm volatile(
;             "ds_read_b128 %0, %12\n\tds_read_b128 %1, %12 offset:1024\n\tds_read_b128 %2, %12 offset:2048\n\tds_read_b128 %3, %12 offset:3072\n\t"
;             "ds_read_b128 %4, %13\n\tds_read_b128 %5, %13 offset:1024\n\tds_read_b128 %6, %13 offset:2048\n\tds_read_b128 %7, %13 offset:3072\n\t"
;             "ds_read_b128 %8, %13 offset:4096\n\tds_read_b128 %9, %13 offset:5120\n\tds_read_b128 %10, %13 offset:6144\n\tds_read_b128 %11, %13 offset:7168\n\t"
;             "s_waitcnt lgkmcnt(4)"
;             : "=&v"(Bl[0]), "=&v"(Bl[1]), "=&v"(Bl[2]), "=&v"(Bl[3]), "=&v"(At[0]), "=&v"(At[1]), "=&v"(At[2]), "=&v"(At[3]),
;               "=&v"(At[4]), "=&v"(At[5]), "=&v"(At[6]), "=&v"(At[7])
;             : "v"(bb), "v"(ab)
;             : "memory");
;       }
;       __builtin_amdgcn_s_setprio(1);
; #pragma unroll
;       for (int m = 0; m < 4; ++m)
; #pragma unroll
;         for (int n = 0; n < 4; ++n) acc[m][n] = __builtin_amdgcn_mfma_f32_16x16x32_bf16(Bl[n], At[m], acc[m][n], 0, 0, 0);
;       __builtin_amdgcn_sched_barrier(0);
;       asm volatile("s_waitcnt lgkmcnt(0)" : "+v"(At[4]), "+v"(At[5]), "+v"(At[6]), "+v"(At[7]) :: "memory");
;       __builtin_amdgcn_sched_barrier(0);
; #pragma unroll
;       for (int m = 4; m < 8; ++m)
; #pragma unroll
;         for (int n = 0; n < 4; ++n) acc[m][n] = __builtin_amdgcn_mfma_f32_16x16x32_bf16(Bl[n], At[m], acc[m][n], 0, 0, 0);
;       __builtin_amdgcn_s_setprio(0);
;       if (more) asm volatile("s_waitcnt vmcnt(6)\n\ts_barrier" ::: "memory");
;       else asm volatile("s_waitcnt vmcnt(0)\n\ts_barrier" ::: "memory");
;       buf = (buf == 2) ? 0 : buf + 1; nbuf = (nbuf == 2) ? 0 : nbuf + 1;
;     }
.LBB0_2091:
	v_lshl_add_u32 v138, s49, 13, v143
	v_lshl_add_u32 v139, s49, 14, v142
	ds_read_b128 v[134:137], v138
	ds_read_b128 v[156:159], v138 offset:1024
	ds_read_b128 v[160:163], v138 offset:2048
	ds_read_b128 v[164:167], v138 offset:3072
	ds_read_b128 v[168:171], v139
	ds_read_b128 v[172:175], v139 offset:1024
	ds_read_b128 v[176:179], v139 offset:2048
	ds_read_b128 v[180:183], v139 offset:3072
	ds_read_b128 v[184:187], v139 offset:4096
	ds_read_b128 v[188:191], v139 offset:5120
	ds_read_b128 v[192:195], v139 offset:6144
	ds_read_b128 v[200:203], v139 offset:7168
	s_waitcnt lgkmcnt(7)
	s_setprio 1
	v_mfma_f32_16x16x32_bf16 v[124:127], v[134:137], v[168:171], v[124:127]
	v_mfma_f32_16x16x32_bf16 v[120:123], v[156:159], v[168:171], v[120:123]
	v_mfma_f32_16x16x32_bf16 v[116:119], v[160:163], v[168:171], v[116:119]
	v_mfma_f32_16x16x32_bf16 v[112:115], v[164:167], v[168:171], v[112:115]
	s_waitcnt lgkmcnt(6)
	v_mfma_f32_16x16x32_bf16 v[108:111], v[134:137], v[172:175], v[108:111]
	v_mfma_f32_16x16x32_bf16 v[104:107], v[156:159], v[172:175], v[104:107]
	v_mfma_f32_16x16x32_bf16 v[100:103], v[160:163], v[172:175], v[100:103]
	v_mfma_f32_16x16x32_bf16 v[96:99], v[164:167], v[172:175], v[96:99]
	s_waitcnt lgkmcnt(5)
	v_mfma_f32_16x16x32_bf16 v[92:95], v[134:137], v[176:179], v[92:95]
	v_mfma_f32_16x16x32_bf16 v[88:91], v[156:159], v[176:179], v[88:91]
	v_mfma_f32_16x16x32_bf16 v[84:87], v[160:163], v[176:179], v[84:87]
	v_mfma_f32_16x16x32_bf16 v[80:83], v[164:167], v[176:179], v[80:83]
	s_waitcnt lgkmcnt(4)
	v_mfma_f32_16x16x32_bf16 v[76:79], v[134:137], v[180:183], v[76:79]
	v_mfma_f32_16x16x32_bf16 v[72:75], v[156:159], v[180:183], v[72:75]
	v_mfma_f32_16x16x32_bf16 v[68:71], v[160:163], v[180:183], v[68:71]
	v_mfma_f32_16x16x32_bf16 v[64:67], v[164:167], v[180:183], v[64:67]
	s_waitcnt lgkmcnt(3)
	s_nop 0
	v_mfma_f32_16x16x32_bf16 v[60:63], v[134:137], v[184:187], v[60:63]
	v_mfma_f32_16x16x32_bf16 v[56:59], v[156:159], v[184:187], v[56:59]
	v_mfma_f32_16x16x32_bf16 v[52:55], v[160:163], v[184:187], v[52:55]
	v_mfma_f32_16x16x32_bf16 v[48:51], v[164:167], v[184:187], v[48:51]
	s_waitcnt lgkmcnt(2)
	v_mfma_f32_16x16x32_bf16 v[44:47], v[134:137], v[188:191], v[44:47]
	v_mfma_f32_16x16x32_bf16 v[40:43], v[156:159], v[188:191], v[40:43]
	v_mfma_f32_16x16x32_bf16 v[36:39], v[160:163], v[188:191], v[36:39]
	v_mfma_f32_16x16x32_bf16 v[32:35], v[164:167], v[188:191], v[32:35]
	s_waitcnt lgkmcnt(1)
	v_mfma_f32_16x16x32_bf16 v[20:23], v[134:137], v[192:195], v[20:23]
	v_mfma_f32_16x16x32_bf16 v[8:11], v[156:159], v[192:195], v[8:11]
	v_mfma_f32_16x16x32_bf16 v[4:7], v[160:163], v[192:195], v[4:7]
	v_mfma_f32_16x16x32_bf16 v[0:3], v[164:167], v[192:195], v[0:3]
	s_waitcnt lgkmcnt(0)
	v_mfma_f32_16x16x32_bf16 v[28:31], v[134:137], v[200:203], v[28:31]
	v_mfma_f32_16x16x32_bf16 v[24:27], v[156:159], v[200:203], v[24:27]
	v_mfma_f32_16x16x32_bf16 v[16:19], v[160:163], v[200:203], v[16:19]
	v_mfma_f32_16x16x32_bf16 v[12:15], v[164:167], v[200:203], v[12:15]
	s_setprio 0
	s_and_b64 vcc, exec, s[40:41]
	s_cbranch_vccnz .Lgt10_last
	s_add_i32 s40, s49, 1
	s_cmp_lg_u32 s49, 2
	s_cselect_b32 s49, s40, 0
	s_add_i32 s40, s48, 1
	s_cmp_lg_u32 s48, 2
	s_cselect_b32 s48, s40, 0
	s_add_i32 s47, s47, 1
	s_add_u32 s36, s36, 0x2000
	s_addc_u32 s37, s37, 0
	s_add_u32 s38, s38, 0x4000
	s_addc_u32 s39, s39, 0
	s_cmpk_eq_i32 s47, 0x58
	s_waitcnt vmcnt(6)
	s_barrier
	s_branch .LBB0_2089
